# P0 transposer: two items in flight per wave (double data buffer, exact vmcnt cases)
# baseline (speedup 1.0000x reference)
; #define LAS __attribute__((address_space(3)))
; __device__ __forceinline__ void transpose_item(const float* W, const float* g  , int K, int N, bf16* WT, LAS float* scr, int kb, int nb, int lane) {
;     const int k0 = 64 * kb, n0 = 32 * nb;
; #pragma unroll 8
;     for (int i = 0; i < 32; ++i) { const int kk = 2 * i + (lane >> 5); const float gv = g ? g[k0 + kk] : 1.f; scr[kk * 33 + (lane & 31)] = W[(size_t)(k0 + kk) * N + n0 + (lane & 31)] * gv; }
; __device__ __forceinline__ void transpose_tensor(const float* W, const float* g, int gstep, int nl, int K, int N, bf16* WT, LAS float* scr, int gw, int NGW, int lane) {
;     const int nblk = N / 32, per = (K / 64) * nblk, total = nl * per;
;     for (int it = gw; it < total; it += NGW) { const int l = it / per, r = it - l * per;
;         transpose_item(W + (size_t)l * K * N, g ? g + (size_t)l * gstep : nullptr, K, N, WT + (size_t)l * K * N, scr, r / nblk, r % nblk, lane); }
.Lwt_run:
	s_load_dwordx2 s[38:39], s[10:11], s19
	s_load_dwordx2 s[40:41], s[10:11], s20
	s_lshr_b32 s27, s63, 5
	s_lshr_b32 s25, s62, 6
	s_mul_i32 s25, s25, s27
	s_mov_b32 s24, s66
	s_lshl_b32 s30, s63, 8
	s_mul_i32 s29, s62, s63
	s_lshl_b32 s31, s29, 1
	s_lshl_b32 s29, s29, 2
	s_lshl_b32 s32, s62, 6
	s_lshl_b32 s35, s63, 2
	s_lshl_b32 s36, s62, 1
	s_add_u32 s42, s12, s34
	s_addc_u32 s43, s13, 0
	v_mad_u32_u24 v110, v102, s35, v109
	s_lshl_b32 s61, s35, 1
	v_add_u32_e32 v111, s61, v110
	v_add_u32_e32 v112, s61, v111
	v_add_u32_e32 v113, s61, v112
	v_add_u32_e32 v114, s61, v113
	v_add_u32_e32 v115, s61, v114
	v_add_u32_e32 v116, s61, v115
	v_add_u32_e32 v117, s61, v116
	v_add_u32_e32 v118, s61, v117
	v_add_u32_e32 v119, s61, v118
	v_add_u32_e32 v120, s61, v119
	v_add_u32_e32 v121, s61, v120
	v_add_u32_e32 v122, s61, v121
	v_add_u32_e32 v123, s61, v122
	v_add_u32_e32 v124, s61, v123
	v_add_u32_e32 v125, s61, v124
	v_add_u32_e32 v126, s61, v125
	v_add_u32_e32 v127, s61, v126
	v_add_u32_e32 v128, s61, v127
	v_add_u32_e32 v129, s61, v128
	v_add_u32_e32 v130, s61, v129
	v_add_u32_e32 v131, s61, v130
	v_add_u32_e32 v132, s61, v131
	v_add_u32_e32 v133, s61, v132
	v_add_u32_e32 v134, s61, v133
	v_add_u32_e32 v135, s61, v134
	v_add_u32_e32 v136, s61, v135
	v_add_u32_e32 v137, s61, v136
	v_add_u32_e32 v138, s61, v137
	v_add_u32_e32 v139, s61, v138
	v_add_u32_e32 v140, s61, v139
	v_add_u32_e32 v141, s61, v140
	v_mad_u32_u24 v142, v106, s36, v105
	s_lshl_b32 s61, s36, 3
	v_add_u32_e32 v143, s61, v142
	v_add_u32_e32 v144, s61, v143
	v_add_u32_e32 v145, s61, v144
	v_mov_b32_e32 v178, 1.0
	v_mov_b32_e32 v179, 1.0
	v_mov_b32_e32 v180, 1.0
	v_mov_b32_e32 v181, 1.0
	v_mov_b32_e32 v182, 1.0
	v_mov_b32_e32 v183, 1.0
	v_mov_b32_e32 v184, 1.0
	v_mov_b32_e32 v185, 1.0
	s_add_u32 s37, s15, s65
	v_mov_b32_e32 v36, 1.0
	v_mov_b32_e32 v37, 1.0
	v_mov_b32_e32 v38, 1.0
	v_mov_b32_e32 v39, 1.0
	v_mov_b32_e32 v40, 1.0
	v_mov_b32_e32 v41, 1.0
	v_mov_b32_e32 v42, 1.0
	v_mov_b32_e32 v43, 1.0
	s_waitcnt lgkmcnt(0)
	s_add_u32 s40, s40, s21
	s_addc_u32 s41, s41, 0
	s_cmp_lt_u32 s37, s24
	s_cbranch_scc0 .Lwt_next
	s_mul_hi_u32 s54, s37, s26
	s_mul_i32 s55, s54, s25
	s_sub_u32 s55, s37, s55
	s_mul_hi_u32 s56, s55, s28
	s_mul_i32 s57, s56, s27
	s_sub_u32 s57, s55, s57
	s_mul_i32 s58, s54, s29
	s_mul_i32 s61, s56, s30
	s_add_u32 s58, s58, s61
	s_lshl_b32 s61, s57, 7
	s_add_u32 s58, s58, s61
	s_add_u32 s44, s38, s58
	s_addc_u32 s45, s39, 0
	s_mul_i32 s58, s54, s31
	s_mul_i32 s61, s57, s32
	s_add_u32 s58, s58, s61
	s_lshl_b32 s61, s56, 7
	s_add_u32 s58, s58, s61
	s_add_u32 s50, s42, s58
	s_addc_u32 s51, s43, 0
	s_mul_i32 s58, s54, s22
	s_lshl_b32 s61, s56, 8
	s_add_u32 s58, s58, s61
	s_add_u32 s48, s40, s58
	s_addc_u32 s49, s41, 0
	global_load_dword v146, v110, s[44:45] nt
	global_load_dword v147, v111, s[44:45] nt
	global_load_dword v148, v112, s[44:45] nt
	global_load_dword v149, v113, s[44:45] nt
	global_load_dword v150, v114, s[44:45] nt
	global_load_dword v151, v115, s[44:45] nt
	global_load_dword v152, v116, s[44:45] nt
	global_load_dword v153, v117, s[44:45] nt
	global_load_dword v154, v118, s[44:45] nt
	global_load_dword v155, v119, s[44:45] nt
	global_load_dword v156, v120, s[44:45] nt
	global_load_dword v157, v121, s[44:45] nt
	global_load_dword v158, v122, s[44:45] nt
	global_load_dword v159, v123, s[44:45] nt
	global_load_dword v160, v124, s[44:45] nt
	global_load_dword v161, v125, s[44:45] nt
	global_load_dword v162, v126, s[44:45] nt
	global_load_dword v163, v127, s[44:45] nt
	global_load_dword v164, v128, s[44:45] nt
	global_load_dword v165, v129, s[44:45] nt
	global_load_dword v166, v130, s[44:45] nt
	global_load_dword v167, v131, s[44:45] nt
	global_load_dword v168, v132, s[44:45] nt
	global_load_dword v169, v133, s[44:45] nt
	global_load_dword v170, v134, s[44:45] nt
	global_load_dword v171, v135, s[44:45] nt
	global_load_dword v172, v136, s[44:45] nt
	global_load_dword v173, v137, s[44:45] nt
	global_load_dword v174, v138, s[44:45] nt
	global_load_dword v175, v139, s[44:45] nt
	global_load_dword v176, v140, s[44:45] nt
	global_load_dword v177, v141, s[44:45] nt
	s_cmp_eq_u32 s23, 0
	s_cbranch_scc1 .Lwt_nog_a
	global_load_dwordx4 v[178:181], v108, s[48:49]
	global_load_dwordx4 v[182:185], v108, s[48:49] offset:16
	s_branch .Lwt_gd_a
.Lwt_nog_a:
	global_load_dwordx4 v[44:47], v108, s[40:41]
	global_load_dwordx4 v[48:51], v108, s[40:41] offset:16
.Lwt_gd_a:
	s_mov_b32 s75, 0
	s_mov_b32 s76, 0
	s_add_u32 s37, s37, s16
	s_cmp_lt_u32 s37, s24
	s_cbranch_scc0 .Lwt_loop
	s_mul_hi_u32 s54, s37, s26
	s_mul_i32 s55, s54, s25
	s_sub_u32 s55, s37, s55
	s_mul_hi_u32 s56, s55, s28
	s_mul_i32 s57, s56, s27
	s_sub_u32 s57, s55, s57
	s_mul_i32 s58, s54, s29
	s_mul_i32 s61, s56, s30
	s_add_u32 s58, s58, s61
	s_lshl_b32 s61, s57, 7
	s_add_u32 s58, s58, s61
	s_add_u32 s44, s38, s58
	s_addc_u32 s45, s39, 0
	s_mul_i32 s58, s54, s31
	s_mul_i32 s61, s57, s32
	s_add_u32 s58, s58, s61
	s_lshl_b32 s61, s56, 7
	s_add_u32 s58, s58, s61
	s_add_u32 s72, s42, s58
	s_addc_u32 s73, s43, 0
	s_mul_i32 s58, s54, s22
	s_lshl_b32 s61, s56, 8
	s_add_u32 s58, s58, s61
	s_add_u32 s48, s40, s58
	s_addc_u32 s49, s41, 0
	global_load_dword v4, v110, s[44:45] nt
	global_load_dword v5, v111, s[44:45] nt
	global_load_dword v6, v112, s[44:45] nt
	global_load_dword v7, v113, s[44:45] nt
	global_load_dword v8, v114, s[44:45] nt
	global_load_dword v9, v115, s[44:45] nt
	global_load_dword v10, v116, s[44:45] nt
	global_load_dword v11, v117, s[44:45] nt
	global_load_dword v12, v118, s[44:45] nt
	global_load_dword v13, v119, s[44:45] nt
	global_load_dword v14, v120, s[44:45] nt
	global_load_dword v15, v121, s[44:45] nt
	global_load_dword v16, v122, s[44:45] nt
	global_load_dword v17, v123, s[44:45] nt
	global_load_dword v18, v124, s[44:45] nt
	global_load_dword v19, v125, s[44:45] nt
	global_load_dword v20, v126, s[44:45] nt
	global_load_dword v21, v127, s[44:45] nt
	global_load_dword v22, v128, s[44:45] nt
	global_load_dword v23, v129, s[44:45] nt
	global_load_dword v24, v130, s[44:45] nt
	global_load_dword v25, v131, s[44:45] nt
	global_load_dword v26, v132, s[44:45] nt
	global_load_dword v27, v133, s[44:45] nt
	global_load_dword v28, v134, s[44:45] nt
	global_load_dword v29, v135, s[44:45] nt
	global_load_dword v30, v136, s[44:45] nt
	global_load_dword v31, v137, s[44:45] nt
	global_load_dword v32, v138, s[44:45] nt
	global_load_dword v33, v139, s[44:45] nt
	global_load_dword v34, v140, s[44:45] nt
	global_load_dword v35, v141, s[44:45] nt
	s_cmp_eq_u32 s23, 0
	s_cbranch_scc1 .Lwt_nog_b
	global_load_dwordx4 v[36:39], v108, s[48:49]
	global_load_dwordx4 v[40:43], v108, s[48:49] offset:16
	s_branch .Lwt_gd_b

; #define LAS __attribute__((address_space(3)))
; #define LDS_WAIT() asm volatile("s_waitcnt lgkmcnt(0)" ::: "memory")
; __device__ __forceinline__ void transpose_item(const float* W, const float* g  , int K, int N, bf16* WT, LAS float* scr, int kb, int nb, int lane) {
;     const int k0 = 64 * kb, n0 = 32 * nb;
; #pragma unroll 8
;     for (int i = 0; i < 32; ++i) { const int kk = 2 * i + (lane >> 5); const float gv = g ? g[k0 + kk] : 1.f; scr[kk * 33 + (lane & 31)] = W[(size_t)(k0 + kk) * N + n0 + (lane & 31)] * gv; }
;     LDS_WAIT(); asm volatile("" ::: "memory");
.Lwt_gd_b:
	s_mov_b32 s75, 1
.Lwt_loop:
	s_cmp_eq_u32 s75, 0
	s_cbranch_scc1 .Lwt_w0_A
	s_cmp_eq_u32 s76, 0
	s_cbranch_scc1 .Lwt_w34_A
	s_cmp_eq_u32 s76, 1
	s_cbranch_scc1 .Lwt_w38_A
	s_waitcnt vmcnt(42)
	s_branch .Lwt_w1_A
.Lwt_w38_A:
	s_waitcnt vmcnt(38)
	s_branch .Lwt_w1_A
.Lwt_w34_A:
	s_waitcnt vmcnt(34)
	s_branch .Lwt_w1_A

; #define LAS __attribute__((address_space(3)))
; __device__ __forceinline__ void transpose_item(const float* W, const float* g  , int K, int N, bf16* WT, LAS float* scr, int kb, int nb, int lane) {
;     const int k0 = 64 * kb, n0 = 32 * nb;
; #pragma unroll 8
;     for (int i = 0; i < 32; ++i) { const int kk = 2 * i + (lane >> 5); const float gv = g ? g[k0 + kk] : 1.f; scr[kk * 33 + (lane & 31)] = W[(size_t)(k0 + kk) * N + n0 + (lane & 31)] * gv; }
; __device__ __forceinline__ void transpose_tensor(const float* W, const float* g, int gstep, int nl, int K, int N, bf16* WT, LAS float* scr, int gw, int NGW, int lane) {
;     ...
;     for (int it = gw; it < total; it += NGW) { const int l = it / per, r = it - l * per;
;         transpose_item(W + (size_t)l * K * N, g ? g + (size_t)l * gstep : nullptr, K, N, WT + (size_t)l * K * N, scr, r / nblk, r % nblk, lane); }
.Lwt_w1_A:
	s_add_u32 s76, s76, 1
	v_mov_b32_e32 v186, v178
	v_mov_b32_e32 v187, v179
	v_mov_b32_e32 v188, v180
	v_mov_b32_e32 v189, v181
	v_mov_b32_e32 v190, v182
	v_mov_b32_e32 v191, v183
	v_mov_b32_e32 v192, v184
	v_mov_b32_e32 v193, v185
	ds_write_b32 v104, v146
	ds_write_b32 v104, v147 offset:264
	ds_write_b32 v104, v148 offset:528
	ds_write_b32 v104, v149 offset:792
	ds_write_b32 v104, v150 offset:1056
	ds_write_b32 v104, v151 offset:1320
	ds_write_b32 v104, v152 offset:1584
	ds_write_b32 v104, v153 offset:1848
	ds_write_b32 v104, v154 offset:2112
	ds_write_b32 v104, v155 offset:2376
	ds_write_b32 v104, v156 offset:2640
	ds_write_b32 v104, v157 offset:2904
	ds_write_b32 v104, v158 offset:3168
	ds_write_b32 v104, v159 offset:3432
	ds_write_b32 v104, v160 offset:3696
	ds_write_b32 v104, v161 offset:3960
	ds_write_b32 v104, v162 offset:4224
	ds_write_b32 v104, v163 offset:4488
	ds_write_b32 v104, v164 offset:4752
	ds_write_b32 v104, v165 offset:5016
	ds_write_b32 v104, v166 offset:5280
	ds_write_b32 v104, v167 offset:5544
	ds_write_b32 v104, v168 offset:5808
	ds_write_b32 v104, v169 offset:6072
	ds_write_b32 v104, v170 offset:6336
	ds_write_b32 v104, v171 offset:6600
	ds_write_b32 v104, v172 offset:6864
	ds_write_b32 v104, v173 offset:7128
	ds_write_b32 v104, v174 offset:7392
	ds_write_b32 v104, v175 offset:7656
	ds_write_b32 v104, v176 offset:7920
	ds_write_b32 v104, v177 offset:8184
	s_mov_b64 s[52:53], s[50:51]
	s_mov_b32 s74, 0
	s_add_u32 s37, s37, s16
	s_cmp_lt_u32 s37, s24
	s_cbranch_scc0 .Lwt_ni_A
	s_waitcnt lgkmcnt(0)
	s_mul_hi_u32 s54, s37, s26
	s_mul_i32 s55, s54, s25
	s_sub_u32 s55, s37, s55
	s_mul_hi_u32 s56, s55, s28
	s_mul_i32 s57, s56, s27
	s_sub_u32 s57, s55, s57
	s_mul_i32 s58, s54, s29
	s_mul_i32 s61, s56, s30
	s_add_u32 s58, s58, s61
	s_lshl_b32 s61, s57, 7
	s_add_u32 s58, s58, s61
	s_add_u32 s44, s38, s58
	s_addc_u32 s45, s39, 0
	s_mul_i32 s58, s54, s31
	s_mul_i32 s61, s57, s32
	s_add_u32 s58, s58, s61
	s_lshl_b32 s61, s56, 7
	s_add_u32 s58, s58, s61
	s_add_u32 s50, s42, s58
	s_addc_u32 s51, s43, 0
	s_mul_i32 s58, s54, s22
	s_lshl_b32 s61, s56, 8
	s_add_u32 s58, s58, s61
	s_add_u32 s48, s40, s58
	s_addc_u32 s49, s41, 0
	global_load_dword v146, v110, s[44:45] nt
	global_load_dword v147, v111, s[44:45] nt
	global_load_dword v148, v112, s[44:45] nt
	global_load_dword v149, v113, s[44:45] nt
	global_load_dword v150, v114, s[44:45] nt
	global_load_dword v151, v115, s[44:45] nt
	global_load_dword v152, v116, s[44:45] nt
	global_load_dword v153, v117, s[44:45] nt
	global_load_dword v154, v118, s[44:45] nt
	global_load_dword v155, v119, s[44:45] nt
	global_load_dword v156, v120, s[44:45] nt
	global_load_dword v157, v121, s[44:45] nt
	global_load_dword v158, v122, s[44:45] nt
	global_load_dword v159, v123, s[44:45] nt
	global_load_dword v160, v124, s[44:45] nt
	global_load_dword v161, v125, s[44:45] nt
	global_load_dword v162, v126, s[44:45] nt
	global_load_dword v163, v127, s[44:45] nt
	global_load_dword v164, v128, s[44:45] nt
	global_load_dword v165, v129, s[44:45] nt
	global_load_dword v166, v130, s[44:45] nt
	global_load_dword v167, v131, s[44:45] nt
	global_load_dword v168, v132, s[44:45] nt
	global_load_dword v169, v133, s[44:45] nt
	global_load_dword v170, v134, s[44:45] nt
	global_load_dword v171, v135, s[44:45] nt
	global_load_dword v172, v136, s[44:45] nt
	global_load_dword v173, v137, s[44:45] nt
	global_load_dword v174, v138, s[44:45] nt
	global_load_dword v175, v139, s[44:45] nt
	global_load_dword v176, v140, s[44:45] nt
	global_load_dword v177, v141, s[44:45] nt
	s_cmp_eq_u32 s23, 0
	s_cbranch_scc1 .Lwt_nog_c
	global_load_dwordx4 v[178:181], v108, s[48:49]
	global_load_dwordx4 v[182:185], v108, s[48:49] offset:16
	s_branch .Lwt_gd_c

; #define GAS __attribute__((address_space(1)))
; #define LAS __attribute__((address_space(3)))
; #define LDS_WAIT() asm volatile("s_waitcnt lgkmcnt(0)" ::: "memory")
; __device__ __forceinline__ unsigned pk2(float lo, float hi) { return f2bf(lo) | (f2bf(hi) << 16); }
; __device__ __forceinline__ void transpose_item(const float* W, const float* g  , int K, int N, bf16* WT, LAS float* scr, int kb, int nb, int lane) {
;     ...
;     LDS_WAIT(); asm volatile("" ::: "memory");
;     const int c = lane & 7;
; #pragma unroll
;     for (int j = 0; j < 4; ++j) { const int n = (lane >> 3) + 8 * j; const LAS float* s = scr + (8 * c) * 33 + n;
;         v4u o; o.x = pk2(s[0 * 33], s[1 * 33]); o.y = pk2(s[2 * 33], s[3 * 33]); o.z = pk2(s[4 * 33], s[5 * 33]); o.w = pk2(s[6 * 33], s[7 * 33]);
;         *(GAS v4u*)(WT + (size_t)(n0 + n) * K + k0 + 8 * c) = o; }
;     LDS_WAIT(); asm volatile("" ::: "memory");
.Lwt_gd_c:
	s_mov_b32 s74, 1
.Lwt_ni_A:
	s_waitcnt lgkmcnt(0)
	ds_read2_b32 v[194:195], v107 offset0:0 offset1:33
	ds_read2_b32 v[196:197], v107 offset0:66 offset1:99
	ds_read2_b32 v[198:199], v107 offset0:132 offset1:165
	ds_read2_b32 v[200:201], v107 offset0:198 offset1:231
	ds_read2_b32 v[202:203], v107 offset0:8 offset1:41
	ds_read2_b32 v[204:205], v107 offset0:74 offset1:107
	ds_read2_b32 v[206:207], v107 offset0:140 offset1:173
	ds_read2_b32 v[208:209], v107 offset0:206 offset1:239
	ds_read2_b32 v[210:211], v107 offset0:16 offset1:49
	ds_read2_b32 v[212:213], v107 offset0:82 offset1:115
	ds_read2_b32 v[214:215], v107 offset0:148 offset1:181
	ds_read2_b32 v[216:217], v107 offset0:214 offset1:247
	ds_read2_b32 v[218:219], v107 offset0:24 offset1:57
	ds_read2_b32 v[220:221], v107 offset0:90 offset1:123
	ds_read2_b32 v[222:223], v107 offset0:156 offset1:189
	ds_read2_b32 v[224:225], v107 offset0:222 offset1:255
	s_waitcnt lgkmcnt(15)
	v_mul_f32_e32 v194, v186, v194
	v_mul_f32_e32 v195, v187, v195
	v_cvt_pk_bf16_f32 v226, v194, v195
	s_waitcnt lgkmcnt(14)
	v_mul_f32_e32 v196, v188, v196
	v_mul_f32_e32 v197, v189, v197
	v_cvt_pk_bf16_f32 v227, v196, v197
	s_waitcnt lgkmcnt(13)
	v_mul_f32_e32 v198, v190, v198
	v_mul_f32_e32 v199, v191, v199
	v_cvt_pk_bf16_f32 v228, v198, v199
	s_waitcnt lgkmcnt(12)
	v_mul_f32_e32 v200, v192, v200
	v_mul_f32_e32 v201, v193, v201
	v_cvt_pk_bf16_f32 v229, v200, v201
	global_store_dwordx4 v142, v[226:229], s[52:53]
	s_waitcnt lgkmcnt(11)
	v_mul_f32_e32 v202, v186, v202
	v_mul_f32_e32 v203, v187, v203
	v_cvt_pk_bf16_f32 v230, v202, v203
	s_waitcnt lgkmcnt(10)
	v_mul_f32_e32 v204, v188, v204
	v_mul_f32_e32 v205, v189, v205
	v_cvt_pk_bf16_f32 v231, v204, v205
	s_waitcnt lgkmcnt(9)
	v_mul_f32_e32 v206, v190, v206
	v_mul_f32_e32 v207, v191, v207
	v_cvt_pk_bf16_f32 v232, v206, v207
	s_waitcnt lgkmcnt(8)
	v_mul_f32_e32 v208, v192, v208
	v_mul_f32_e32 v209, v193, v209
	v_cvt_pk_bf16_f32 v233, v208, v209
	global_store_dwordx4 v143, v[230:233], s[52:53]
	s_waitcnt lgkmcnt(7)
	v_mul_f32_e32 v210, v186, v210
	v_mul_f32_e32 v211, v187, v211
	v_cvt_pk_bf16_f32 v234, v210, v211
	s_waitcnt lgkmcnt(6)
	v_mul_f32_e32 v212, v188, v212
	v_mul_f32_e32 v213, v189, v213
	v_cvt_pk_bf16_f32 v235, v212, v213
	s_waitcnt lgkmcnt(5)
	v_mul_f32_e32 v214, v190, v214
	v_mul_f32_e32 v215, v191, v215
	v_cvt_pk_bf16_f32 v236, v214, v215
	s_waitcnt lgkmcnt(4)
	v_mul_f32_e32 v216, v192, v216
	v_mul_f32_e32 v217, v193, v217
	v_cvt_pk_bf16_f32 v237, v216, v217
	global_store_dwordx4 v144, v[234:237], s[52:53]
	s_waitcnt lgkmcnt(3)
	v_mul_f32_e32 v218, v186, v218
	v_mul_f32_e32 v219, v187, v219
	v_cvt_pk_bf16_f32 v238, v218, v219
	s_waitcnt lgkmcnt(2)
	v_mul_f32_e32 v220, v188, v220
	v_mul_f32_e32 v221, v189, v221
	v_cvt_pk_bf16_f32 v239, v220, v221
	s_waitcnt lgkmcnt(1)
	v_mul_f32_e32 v222, v190, v222
	v_mul_f32_e32 v223, v191, v223
	v_cvt_pk_bf16_f32 v240, v222, v223
	s_waitcnt lgkmcnt(0)
	v_mul_f32_e32 v224, v192, v224
	v_mul_f32_e32 v225, v193, v225
	v_cvt_pk_bf16_f32 v241, v224, v225
	global_store_dwordx4 v145, v[238:241], s[52:53]
	s_cmp_eq_u32 s75, 0
	s_cbranch_scc1 .Lwt_next
	s_cmp_eq_u32 s74, 0
	s_cbranch_scc1 .Lwt_w0_B
	s_cmp_eq_u32 s76, 0
	s_cbranch_scc1 .Lwt_w34_B
	s_cmp_eq_u32 s76, 1
	s_cbranch_scc1 .Lwt_w38_B
	s_waitcnt vmcnt(42)
	s_branch .Lwt_w1_B

; #define LAS __attribute__((address_space(3)))
; __device__ __forceinline__ void transpose_item(const float* W, const float* g  , int K, int N, bf16* WT, LAS float* scr, int kb, int nb, int lane) {
;     const int k0 = 64 * kb, n0 = 32 * nb;
; #pragma unroll 8
;     for (int i = 0; i < 32; ++i) { const int kk = 2 * i + (lane >> 5); const float gv = g ? g[k0 + kk] : 1.f; scr[kk * 33 + (lane & 31)] = W[(size_t)(k0 + kk) * N + n0 + (lane & 31)] * gv; }
; __device__ __forceinline__ void transpose_tensor(const float* W, const float* g, int gstep, int nl, int K, int N, bf16* WT, LAS float* scr, int gw, int NGW, int lane) {
;     ...
;     for (int it = gw; it < total; it += NGW) { const int l = it / per, r = it - l * per;
;         transpose_item(W + (size_t)l * K * N, g ? g + (size_t)l * gstep : nullptr, K, N, WT + (size_t)l * K * N, scr, r / nblk, r % nblk, lane); }
.Lwt_w1_B:
	s_add_u32 s76, s76, 1
	v_mov_b32_e32 v186, v36
	v_mov_b32_e32 v187, v37
	v_mov_b32_e32 v188, v38
	v_mov_b32_e32 v189, v39
	v_mov_b32_e32 v190, v40
	v_mov_b32_e32 v191, v41
	v_mov_b32_e32 v192, v42
	v_mov_b32_e32 v193, v43
	ds_write_b32 v104, v4
	ds_write_b32 v104, v5 offset:264
	ds_write_b32 v104, v6 offset:528
	ds_write_b32 v104, v7 offset:792
	ds_write_b32 v104, v8 offset:1056
	ds_write_b32 v104, v9 offset:1320
	ds_write_b32 v104, v10 offset:1584
	ds_write_b32 v104, v11 offset:1848
	ds_write_b32 v104, v12 offset:2112
	ds_write_b32 v104, v13 offset:2376
	ds_write_b32 v104, v14 offset:2640
	ds_write_b32 v104, v15 offset:2904
	ds_write_b32 v104, v16 offset:3168
	ds_write_b32 v104, v17 offset:3432
	ds_write_b32 v104, v18 offset:3696
	ds_write_b32 v104, v19 offset:3960
	ds_write_b32 v104, v20 offset:4224
	ds_write_b32 v104, v21 offset:4488
	ds_write_b32 v104, v22 offset:4752
	ds_write_b32 v104, v23 offset:5016
	ds_write_b32 v104, v24 offset:5280
	ds_write_b32 v104, v25 offset:5544
	ds_write_b32 v104, v26 offset:5808
	ds_write_b32 v104, v27 offset:6072
	ds_write_b32 v104, v28 offset:6336
	ds_write_b32 v104, v29 offset:6600
	ds_write_b32 v104, v30 offset:6864
	ds_write_b32 v104, v31 offset:7128
	ds_write_b32 v104, v32 offset:7392
	ds_write_b32 v104, v33 offset:7656
	ds_write_b32 v104, v34 offset:7920
	ds_write_b32 v104, v35 offset:8184
	s_mov_b64 s[52:53], s[72:73]
	s_mov_b32 s75, 0
	s_add_u32 s37, s37, s16
	s_cmp_lt_u32 s37, s24
	s_cbranch_scc0 .Lwt_ni_B
	s_waitcnt lgkmcnt(0)
	s_mul_hi_u32 s54, s37, s26
	s_mul_i32 s55, s54, s25
	s_sub_u32 s55, s37, s55
	s_mul_hi_u32 s56, s55, s28
	s_mul_i32 s57, s56, s27
	s_sub_u32 s57, s55, s57
	s_mul_i32 s58, s54, s29
	s_mul_i32 s61, s56, s30
	s_add_u32 s58, s58, s61
	s_lshl_b32 s61, s57, 7
	s_add_u32 s58, s58, s61
	s_add_u32 s44, s38, s58
	s_addc_u32 s45, s39, 0
	s_mul_i32 s58, s54, s31
	s_mul_i32 s61, s57, s32
	s_add_u32 s58, s58, s61
	s_lshl_b32 s61, s56, 7
	s_add_u32 s58, s58, s61
	s_add_u32 s72, s42, s58
	s_addc_u32 s73, s43, 0
	s_mul_i32 s58, s54, s22
	s_lshl_b32 s61, s56, 8
	s_add_u32 s58, s58, s61
	s_add_u32 s48, s40, s58
	s_addc_u32 s49, s41, 0
	global_load_dword v4, v110, s[44:45] nt
	global_load_dword v5, v111, s[44:45] nt
	global_load_dword v6, v112, s[44:45] nt
	global_load_dword v7, v113, s[44:45] nt
	global_load_dword v8, v114, s[44:45] nt
	global_load_dword v9, v115, s[44:45] nt
	global_load_dword v10, v116, s[44:45] nt
	global_load_dword v11, v117, s[44:45] nt
	global_load_dword v12, v118, s[44:45] nt
	global_load_dword v13, v119, s[44:45] nt
	global_load_dword v14, v120, s[44:45] nt
	global_load_dword v15, v121, s[44:45] nt
	global_load_dword v16, v122, s[44:45] nt
	global_load_dword v17, v123, s[44:45] nt
	global_load_dword v18, v124, s[44:45] nt
	global_load_dword v19, v125, s[44:45] nt
	global_load_dword v20, v126, s[44:45] nt
	global_load_dword v21, v127, s[44:45] nt
	global_load_dword v22, v128, s[44:45] nt
	global_load_dword v23, v129, s[44:45] nt
	global_load_dword v24, v130, s[44:45] nt
	global_load_dword v25, v131, s[44:45] nt
	global_load_dword v26, v132, s[44:45] nt
	global_load_dword v27, v133, s[44:45] nt
	global_load_dword v28, v134, s[44:45] nt
	global_load_dword v29, v135, s[44:45] nt
	global_load_dword v30, v136, s[44:45] nt
	global_load_dword v31, v137, s[44:45] nt
	global_load_dword v32, v138, s[44:45] nt
	global_load_dword v33, v139, s[44:45] nt
	global_load_dword v34, v140, s[44:45] nt
	global_load_dword v35, v141, s[44:45] nt
	s_cmp_eq_u32 s23, 0
	s_cbranch_scc1 .Lwt_nog_d
	global_load_dwordx4 v[36:39], v108, s[48:49]
	global_load_dwordx4 v[40:43], v108, s[48:49] offset:16
	s_branch .Lwt_gd_d

; #define GAS __attribute__((address_space(1)))
; #define LAS __attribute__((address_space(3)))
; #define LDS_WAIT() asm volatile("s_waitcnt lgkmcnt(0)" ::: "memory")
; __device__ __forceinline__ unsigned pk2(float lo, float hi) { return f2bf(lo) | (f2bf(hi) << 16); }
; __device__ __forceinline__ void transpose_item(const float* W, const float* g  , int K, int N, bf16* WT, LAS float* scr, int kb, int nb, int lane) {
;     ...
;     LDS_WAIT(); asm volatile("" ::: "memory");
;     const int c = lane & 7;
; #pragma unroll
;     for (int j = 0; j < 4; ++j) { const int n = (lane >> 3) + 8 * j; const LAS float* s = scr + (8 * c) * 33 + n;
;         v4u o; o.x = pk2(s[0 * 33], s[1 * 33]); o.y = pk2(s[2 * 33], s[3 * 33]); o.z = pk2(s[4 * 33], s[5 * 33]); o.w = pk2(s[6 * 33], s[7 * 33]);
;         *(GAS v4u*)(WT + (size_t)(n0 + n) * K + k0 + 8 * c) = o; }
;     LDS_WAIT(); asm volatile("" ::: "memory");
.Lwt_ni_B:
	s_waitcnt lgkmcnt(0)
	ds_read2_b32 v[194:195], v107 offset0:0 offset1:33
	ds_read2_b32 v[196:197], v107 offset0:66 offset1:99
	ds_read2_b32 v[198:199], v107 offset0:132 offset1:165
	ds_read2_b32 v[200:201], v107 offset0:198 offset1:231
	ds_read2_b32 v[202:203], v107 offset0:8 offset1:41
	ds_read2_b32 v[204:205], v107 offset0:74 offset1:107
	ds_read2_b32 v[206:207], v107 offset0:140 offset1:173
	ds_read2_b32 v[208:209], v107 offset0:206 offset1:239
	ds_read2_b32 v[210:211], v107 offset0:16 offset1:49
	ds_read2_b32 v[212:213], v107 offset0:82 offset1:115
	ds_read2_b32 v[214:215], v107 offset0:148 offset1:181
	ds_read2_b32 v[216:217], v107 offset0:214 offset1:247
	ds_read2_b32 v[218:219], v107 offset0:24 offset1:57
	ds_read2_b32 v[220:221], v107 offset0:90 offset1:123
	ds_read2_b32 v[222:223], v107 offset0:156 offset1:189
	ds_read2_b32 v[224:225], v107 offset0:222 offset1:255
	s_waitcnt lgkmcnt(15)
	v_mul_f32_e32 v194, v186, v194
	v_mul_f32_e32 v195, v187, v195
	v_cvt_pk_bf16_f32 v226, v194, v195
	s_waitcnt lgkmcnt(14)
	v_mul_f32_e32 v196, v188, v196
	v_mul_f32_e32 v197, v189, v197
	v_cvt_pk_bf16_f32 v227, v196, v197
	s_waitcnt lgkmcnt(13)
	v_mul_f32_e32 v198, v190, v198
	v_mul_f32_e32 v199, v191, v199
	v_cvt_pk_bf16_f32 v228, v198, v199
	s_waitcnt lgkmcnt(12)
	v_mul_f32_e32 v200, v192, v200
	v_mul_f32_e32 v201, v193, v201
	v_cvt_pk_bf16_f32 v229, v200, v201
	global_store_dwordx4 v142, v[226:229], s[52:53]
	s_waitcnt lgkmcnt(11)
	v_mul_f32_e32 v202, v186, v202
	v_mul_f32_e32 v203, v187, v203
	v_cvt_pk_bf16_f32 v230, v202, v203
	s_waitcnt lgkmcnt(10)
	v_mul_f32_e32 v204, v188, v204
	v_mul_f32_e32 v205, v189, v205
	v_cvt_pk_bf16_f32 v231, v204, v205
	s_waitcnt lgkmcnt(9)
	v_mul_f32_e32 v206, v190, v206
	v_mul_f32_e32 v207, v191, v207
	v_cvt_pk_bf16_f32 v232, v206, v207
	s_waitcnt lgkmcnt(8)
	v_mul_f32_e32 v208, v192, v208
	v_mul_f32_e32 v209, v193, v209
	v_cvt_pk_bf16_f32 v233, v208, v209
	global_store_dwordx4 v143, v[230:233], s[52:53]
	s_waitcnt lgkmcnt(7)
	v_mul_f32_e32 v210, v186, v210
	v_mul_f32_e32 v211, v187, v211
	v_cvt_pk_bf16_f32 v234, v210, v211
	s_waitcnt lgkmcnt(6)
	v_mul_f32_e32 v212, v188, v212
	v_mul_f32_e32 v213, v189, v213
	v_cvt_pk_bf16_f32 v235, v212, v213
	s_waitcnt lgkmcnt(5)
	v_mul_f32_e32 v214, v190, v214
	v_mul_f32_e32 v215, v191, v215
	v_cvt_pk_bf16_f32 v236, v214, v215
	s_waitcnt lgkmcnt(4)
	v_mul_f32_e32 v216, v192, v216
	v_mul_f32_e32 v217, v193, v217
	v_cvt_pk_bf16_f32 v237, v216, v217
	global_store_dwordx4 v144, v[234:237], s[52:53]
	s_waitcnt lgkmcnt(3)
	v_mul_f32_e32 v218, v186, v218
	v_mul_f32_e32 v219, v187, v219
	v_cvt_pk_bf16_f32 v238, v218, v219
	s_waitcnt lgkmcnt(2)
	v_mul_f32_e32 v220, v188, v220
	v_mul_f32_e32 v221, v189, v221
	v_cvt_pk_bf16_f32 v239, v220, v221
	s_waitcnt lgkmcnt(1)
	v_mul_f32_e32 v222, v190, v222
	v_mul_f32_e32 v223, v191, v223
	v_cvt_pk_bf16_f32 v240, v222, v223
	s_waitcnt lgkmcnt(0)
	v_mul_f32_e32 v224, v192, v224
	v_mul_f32_e32 v225, v193, v225
	v_cvt_pk_bf16_f32 v241, v224, v225
	global_store_dwordx4 v145, v[238:241], s[52:53]
	s_cmp_eq_u32 s74, 0
	s_cbranch_scc1 .Lwt_next
	s_branch .Lwt_loop
